# P4: weight-transpose share first, split 2:1 in two classes; scan steady-state fast path (scalar-base image loads, running V pointers, one counted vmcnt)
# baseline (speedup 1.0000x reference)
; __device__ __forceinline__ int tid_of(int wave_id) { int t = wave_id * 64 + lane_id(); asm volatile("" : "+v"(t)); return t; }
; #define ATT_BAR() do { asm volatile("s_waitcnt lgkmcnt(0)" ::: "memory"); __builtin_amdgcn_s_barrier(); asm volatile("" ::: "memory"); } while (0)
; __device__ __forceinline__ void hgrn_scan(const Params& p, LAS unsigned char* lds, int chain) {
;     int tid_o = tid_of(p.wave_id);
;     const int tid = tid_o, lane = tid & 63, wave = __builtin_amdgcn_readfirstlane(tid >> 6);
;     const int li = lane & 15, g = lane >> 4, qq = li >> 2, pp = li & 3;
;     const int dir = chain / (BATCH * NHEAD), b = (chain / NHEAD) % BATCH, h = chain % NHEAD;
;     const bf16* IA = (const bf16*)(p.ws + WS_IA) + h * HD;
;     bf16* O = (bf16*)(p.ws + (dir == 0 ? WS_OF2 : WS_OB2)) + h * HD + 16 * wave + 4 * g;
;     const long ost = dir ? -(long)WA : (long)WA;
;     const unsigned char* img0 = p.ws + WS_HIMG + (size_t)chain * NCH * HIMG_BYTES;
;     f32x4 S[8];
; #pragma unroll
;     for (int i = 0; i < 8; ++i) S[i] = (f32x4){0.f, 0.f, 0.f, 0.f};
;     u32x4 rq[2][2], rk[2][2], rp[2], rd[2], rv[2][2];
;     ...
;     HS_LOAD(0, 0); HS_LOAD(1, 1);
;     HS_STORE(0, 0);
;     HS_LOAD(2, 0);
;     ATT_BAR();
; #pragma unroll 1
;     for (int c2 = 0; c2 < NCH; c2 += 2) {
.LBB0_405:
	s_or_b64 exec, exec, s[12:13]
	s_movk_i32 s12, 0x120
	v_mul_lo_u32 v46, v132, s12
	s_mov_b32 s18, 0x6542000
	s_and_b64 s[12:13], s[6:7], exec
	s_cselect_b32 s12, s18, 0x8942000
	s_add_u32 s12, s26, s12
	s_addc_u32 s21, s27, 0
	s_ashr_i32 s18, s20, 2
	s_and_b32 s18, s18, -16
	s_ashr_i32 s19, s18, 31
	s_lshl_b64 s[38:39], s[16:17], 4
	s_add_u32 s12, s12, s38
	v_lshrrev_b32_e32 v32, 2, v47
	s_addc_u32 s20, s21, s39
	s_lshl_b64 s[16:17], s[18:19], 5
	v_and_b32_e32 v52, 12, v32
	s_add_u32 s16, s12, s16
	v_mov_b32_e32 v115, 0
	s_addc_u32 s17, s20, s17
	v_lshlrev_b32_e32 v116, 1, v52
	v_mov_b32_e32 v117, v115
	s_movk_i32 s12, 0x80
	s_and_b64 s[38:39], s[6:7], exec
	s_cselect_b32 s38, 0, 0x7800
	s_sub_u32 s16, s16, s38
	s_subb_u32 s17, s17, 0
	v_and_b32_e32 v237, 15, v47
	v_sub_u32_e32 v238, 15, v237
	v_cndmask_b32_e64 v238, v238, v237, s[6:7]
	v_lshl_add_u32 v238, v238, 5, v116
	v_mov_b32_e32 v239, 0
	v_lshl_add_u64 v[44:45], s[16:17], 0, v[238:239]
	v_mov_b32_e32 v117, 0x8ff
	v_mov_b32_e32 v138, 0xff
	v_cmp_gt_i32_e32 vcc, s12, v132
	v_add_u32_e32 v34, 0x80, v132
	v_add_u32_e32 v32, 0xffffff80, v132
	v_cndmask_b32_e32 v35, v117, v138, vcc
	v_cndmask_b32_e32 v36, v32, v34, vcc
	v_mov_b32_e32 v32, s11
	v_sub_u32_e32 v34, v35, v34
	v_cndmask_b32_e64 v33, v32, 0, vcc
	v_mov_b32_e32 v32, s10
	v_mov_b32_e32 v37, s3
	v_cndmask_b32_e64 v34, v34, v36, s[6:7]
	v_cndmask_b32_e32 v32, v32, v37, vcc
	v_ashrrev_i32_e32 v35, 31, v34
	v_lshl_add_u64 v[32:33], v[32:33], 0, v[34:35]
	v_lshlrev_b64 v[32:33], 11, v[32:33]
	v_lshl_add_u64 v[32:33], s[8:9], 0, v[32:33]
	v_lshl_add_u64 v[50:51], v[32:33], 0, v[114:115]
	global_load_dwordx4 v[32:35], v[50:51], off offset:16
	global_load_dwordx4 v[36:39], v[50:51], off
	s_movk_i32 s16, 0xa0
	v_lshlrev_b32_e32 v50, 3, v47
	s_lshl_b32 s12, s18, 1
	v_mul_lo_u32 v51, v132, s16
	s_movk_i32 s16, 0x90
	s_lshl_b64 s[14:15], s[14:15], 22
	v_and_b32_e32 v49, 15, v47
	v_and_b32_e32 v50, 24, v50
	v_mul_lo_u32 v53, v132, s16
	v_lshl_add_u64 v[118:119], v[44:45], 0, s[14:15]
	s_movk_i32 s16, 0x400
	s_and_b64 s[14:15], s[6:7], exec
	v_add_u32_e32 v139, 0, v50
	v_or_b32_e32 v56, 16, v49
	v_or_b32_e32 v57, 32, v49
	v_or_b32_e32 v58, 48, v49
	s_cselect_b32 s14, s16, 0xfffffc00
	s_add_i32 s17, 0, 0x1d400
	v_add_u32_e32 v54, s12, v139
	v_bfe_u32 v47, v47, 2, 4
	v_mov_b32_e32 v120, 0
	v_mov_b32_e32 v121, 0
	s_lshl_b32 s38, s14, 4
	s_ashr_i32 s39, s14, 31
	v_mov_b32_e32 v122, s38
	v_mov_b32_e32 v123, s39
	s_lshl_b32 s38, s14, 5
	v_mov_b32_e32 v124, s38
	v_mov_b32_e32 v125, s39
	s_mul_i32 s38, s14, 48
	v_mov_b32_e32 v126, s38
	v_mov_b32_e32 v127, s39
	s_add_i32 s14, 0, 0x10e00
	s_add_i32 s15, 0, 0x1ae00
	s_add_i32 s16, 0, 0x15e00
	s_add_i32 s12, s12, s17
	s_waitcnt lgkmcnt(0)
	s_barrier
	v_mul_u32_u24_e32 v55, 0x120, v47
	v_mul_u32_u24_e32 v141, 0xa0, v47
	v_add_u32_e32 v44, s14, v51
	v_add_u32_e32 v47, s16, v48
	v_add_u32_e32 v152, s17, v46
	v_add_u32_e32 v46, s12, v50
	v_add_u32_e32 v48, s14, v50
	v_add_u32_e32 v154, 0, v51
	v_lshlrev_b32_e32 v50, 4, v132
	s_add_u32 s14, s26, s23
	v_mul_u32_u24_e32 v142, 0x90, v49
	v_lshlrev_b32_e32 v143, 2, v52
	v_mul_u32_u24_e32 v144, 0x88, v49
	v_add_u32_e32 v45, s15, v53
	v_add_u32_e32 v49, s15, v116
	v_sub_u32_e32 v50, v154, v50
	s_addc_u32 s15, s27, s22
	s_mov_b32 s13, 0
	s_movk_i32 s20, 0x8ff
	v_add_u32_e32 v140, 0, v116
	v_or_b32_e32 v145, 64, v143
	v_or_b32_e32 v146, 0x80, v143
	v_or_b32_e32 v147, 0xc0, v143
	s_movk_i32 s21, 0x100
	v_or_b32_e32 v148, 0x100, v143
	v_or_b32_e32 v149, 0x140, v143
	v_or_b32_e32 v150, 0x180, v143
	v_or_b32_e32 v151, 0x1c0, v143
	v_add_u32_e32 v153, s16, v116
	v_mul_u32_u24_e32 v155, 0x88, v56
	v_sub_u32_e32 v156, 0, v132
	v_lshl_add_u64 v[128:129], s[14:15], 0, v[40:41]
	v_lshl_add_u64 v[130:131], s[14:15], 0, v[42:43]
	s_mov_b64 s[34:35], s[14:15]
	v_mov_b32_e32 v240, v40
	v_mov_b32_e32 v241, v42
	s_mov_b32 s36, 0xfffc0000
	s_and_b64 s[96:97], s[6:7], exec
	s_cselect_b32 s36, 0x40000, s36
	s_cselect_b32 s37, 0, -1
	s_mov_b64 s[14:15], 0
	s_movk_i32 s22, 0xff00
	s_mov_b32 s30, -2
	v_add_u32_e32 v157, v54, v55
	v_add_u32_e32 v158, v44, v113
	v_add_u32_e32 v159, v45, v113
	v_add_u32_e32 v160, v47, v113
	v_add_u32_e32 v161, v46, v55
	v_add_u32_e32 v162, v48, v141
	v_add_u32_e32 v163, v49, v142
	v_add_u32_e32 v164, v50, v113
	v_mov_b32_e32 v68, v115
	v_mov_b32_e32 v69, v115
	v_mov_b32_e32 v70, v115
	v_mov_b32_e32 v71, v115
	v_mov_b32_e32 v64, v115
	v_mov_b32_e32 v65, v115
	v_mov_b32_e32 v66, v115
	v_mov_b32_e32 v67, v115
	v_mov_b32_e32 v84, v115
	v_mov_b32_e32 v85, v115
	v_mov_b32_e32 v86, v115
	v_mov_b32_e32 v87, v115
	v_mov_b32_e32 v72, v115
	v_mov_b32_e32 v73, v115
	v_mov_b32_e32 v74, v115
	v_mov_b32_e32 v75, v115
	v_mov_b32_e32 v88, v115
	v_mov_b32_e32 v89, v115
	v_mov_b32_e32 v90, v115
	v_mov_b32_e32 v91, v115
	v_mov_b32_e32 v80, v115
	v_mov_b32_e32 v81, v115
	v_mov_b32_e32 v82, v115
	v_mov_b32_e32 v83, v115
	v_mov_b32_e32 v92, v115
	v_mov_b32_e32 v93, v115
	v_mov_b32_e32 v94, v115
	v_mov_b32_e32 v95, v115
	v_mov_b32_e32 v76, v115
	v_mov_b32_e32 v77, v115
	v_mov_b32_e32 v78, v115
	v_mov_b32_e32 v79, v115
	s_branch .LBB0_408
.LBB0_406:
	s_or_b64 exec, exec, s[16:17]
	v_add_u32_e32 v32, s22, v132
	v_add_u32_e32 v33, 0x200, v32
	v_cmp_gt_i32_e32 vcc, s21, v33
	v_add_u32_e32 v32, 0x100, v32
	s_waitcnt vmcnt(5)
	v_mov_b32_e32 v36, s3
	v_cndmask_b32_e32 v34, v117, v138, vcc
	v_add3_u32 v34, v156, v34, s20
	v_cndmask_b32_e32 v35, v32, v33, vcc
	v_mov_b32_e32 v32, s11
	v_add_u32_e32 v34, 0xfffff601, v34
	v_cndmask_b32_e64 v33, v32, 0, vcc
	v_mov_b32_e32 v32, s10
	v_cndmask_b32_e64 v34, v34, v35, s[6:7]
	v_cndmask_b32_e32 v32, v32, v36, vcc
	v_ashrrev_i32_e32 v35, 31, v34
	v_lshl_add_u64 v[32:33], v[32:33], 0, v[34:35]
	v_lshlrev_b64 v[32:33], 11, v[32:33]
	v_lshl_add_u64 v[32:33], s[8:9], 0, v[32:33]
	v_lshl_add_u64 v[36:37], v[32:33], 0, v[114:115]
	v_mov_b32_e32 v238, v36
	v_mov_b32_e32 v239, v37
	global_load_dwordx4 v[32:35], v[36:37], off offset:16
	s_nop 0
	global_load_dwordx4 v[36:39], v[36:37], off

; #define LAS __attribute__((address_space(3)))
; __device__ __forceinline__ void hgrn_scan(const Params& p, LAS unsigned char* lds, int chain) {
;     ...
; #pragma unroll
;         for (int blk = 0; blk < 8; ++blk) {
;             const f32x4 d4 = *(const LAS f32x4*)(bb + SB_D + (16 * blk + 4 * g) * 4);
;             f32x4 s = S[blk] * d4;
; #pragma unroll
;             for (int sp = 0; sp < 2; ++sp) {
;                 const LAS unsigned char* kp = bb + SB_KD + (16 * blk + li) * HPK + (32 * sp + 4 * g) * 2;
;                 s = __builtin_amdgcn_mfma_f32_16x16x32_bf16(cat8u(*(const LAS u32x2*)kp, *(const LAS u32x2*)(kp + 32)), vf[sp], s, 0, 0, 0);
;             }
;             S[blk] = s;
;         }
;         if (c + 1 < NCH) HS_STORE(c + 1, (uu + 1) & 1);
;         if (c + 3 < NCH) HS_LOAD(c + 3, (uu + 1) & 1);
.LBB0_412:
	v_add_u32_e32 v165, v140, v144
	v_add_u32_e32 v174, v140, v116
	ds_read_b128 v[180:183], v174 offset:50176
	ds_read_b64 v[184:185], v165 offset:20480
	ds_read_b64 v[186:187], v165 offset:20512
	ds_read_b64 v[188:189], v165 offset:20544
	ds_read_b64 v[190:191], v165 offset:20576
	ds_read_b128 v[192:195], v174 offset:50240
	ds_read_b64 v[196:197], v165 offset:22656
	ds_read_b64 v[198:199], v165 offset:22688
	ds_read_b64 v[200:201], v165 offset:22720
	ds_read_b64 v[202:203], v165 offset:22752
	s_waitcnt lgkmcnt(10)
	ds_read_b128 v[204:207], v174 offset:50304
	ds_read_b64 v[208:209], v165 offset:24832
	ds_read_b64 v[210:211], v165 offset:24864
	ds_read_b64 v[212:213], v165 offset:24896
	ds_read_b64 v[214:215], v165 offset:24928
	s_waitcnt lgkmcnt(5)
	v_pk_mul_f32 v[76:77], v[76:77], v[180:181]
	v_pk_mul_f32 v[78:79], v[78:79], v[182:183]
	v_pk_mul_f32 v[92:93], v[92:93], v[192:193]
	v_pk_mul_f32 v[94:95], v[94:95], v[194:195]
	v_mfma_f32_16x16x32_bf16 v[76:79], v[184:187], v[100:103], v[76:79]
	s_nop 0
	v_mfma_f32_16x16x32_bf16 v[92:95], v[196:199], v[100:103], v[92:95]
	v_mfma_f32_16x16x32_bf16 v[76:79], v[188:191], v[96:99], v[76:79]
	v_mfma_f32_16x16x32_bf16 v[92:95], v[200:203], v[96:99], v[92:95]
	ds_read_b128 v[180:183], v174 offset:50368
	ds_read_b64 v[184:185], v165 offset:27008
	ds_read_b64 v[186:187], v165 offset:27040
	ds_read_b64 v[188:189], v165 offset:27072
	ds_read_b64 v[190:191], v165 offset:27104
	ds_read_b128 v[192:195], v174 offset:50432
	ds_read_b64 v[196:197], v165 offset:29184
	ds_read_b64 v[198:199], v165 offset:29216
	ds_read_b64 v[200:201], v165 offset:29248
	ds_read_b64 v[202:203], v165 offset:29280
	s_waitcnt lgkmcnt(5)
	v_pk_mul_f32 v[80:81], v[80:81], v[204:205]
	v_pk_mul_f32 v[82:83], v[82:83], v[206:207]
	v_pk_mul_f32 v[88:89], v[88:89], v[180:181]
	v_pk_mul_f32 v[90:91], v[90:91], v[182:183]
	v_mfma_f32_16x16x32_bf16 v[80:83], v[208:211], v[100:103], v[80:83]
	s_nop 0
	v_mfma_f32_16x16x32_bf16 v[88:91], v[184:187], v[100:103], v[88:91]
	v_mfma_f32_16x16x32_bf16 v[80:83], v[212:215], v[96:99], v[80:83]
	v_mfma_f32_16x16x32_bf16 v[88:91], v[188:191], v[96:99], v[88:91]
	ds_read_b128 v[204:207], v174 offset:50496
	ds_read_b64 v[208:209], v165 offset:31360
	ds_read_b64 v[210:211], v165 offset:31392
	ds_read_b64 v[212:213], v165 offset:31424
	ds_read_b64 v[214:215], v165 offset:31456
	ds_read_b128 v[180:183], v174 offset:50560
	ds_read_b64 v[184:185], v165 offset:33536
	ds_read_b64 v[186:187], v165 offset:33568
	ds_read_b64 v[188:189], v165 offset:33600
	ds_read_b64 v[190:191], v165 offset:33632
	s_waitcnt lgkmcnt(5)
	v_pk_mul_f32 v[72:73], v[72:73], v[192:193]
	v_pk_mul_f32 v[74:75], v[74:75], v[194:195]
	v_pk_mul_f32 v[84:85], v[84:85], v[204:205]
	v_pk_mul_f32 v[86:87], v[86:87], v[206:207]
	v_mfma_f32_16x16x32_bf16 v[72:75], v[196:199], v[100:103], v[72:75]
	s_nop 0
	v_mfma_f32_16x16x32_bf16 v[84:87], v[208:211], v[100:103], v[84:87]
	v_mfma_f32_16x16x32_bf16 v[72:75], v[200:203], v[96:99], v[72:75]
	v_mfma_f32_16x16x32_bf16 v[84:87], v[212:215], v[96:99], v[84:87]
	ds_read_b128 v[192:195], v174 offset:50624
	ds_read_b64 v[196:197], v165 offset:35712
	ds_read_b64 v[198:199], v165 offset:35744
	ds_read_b64 v[200:201], v165 offset:35776
	ds_read_b64 v[202:203], v165 offset:35808
	s_waitcnt lgkmcnt(0)
	v_pk_mul_f32 v[64:65], v[64:65], v[180:181]
	v_pk_mul_f32 v[66:67], v[66:67], v[182:183]
	v_pk_mul_f32 v[68:69], v[68:69], v[192:193]
	v_pk_mul_f32 v[70:71], v[70:71], v[194:195]
	v_mfma_f32_16x16x32_bf16 v[64:67], v[184:187], v[100:103], v[64:67]
	s_nop 0
	v_mfma_f32_16x16x32_bf16 v[68:71], v[196:199], v[100:103], v[68:71]
	v_mfma_f32_16x16x32_bf16 v[64:67], v[188:191], v[96:99], v[64:67]
	v_mfma_f32_16x16x32_bf16 v[68:71], v[200:203], v[96:99], v[68:71]
	s_sub_u32 s97, s23, 6
	s_cmp_le_u32 s97, 24
	s_cbranch_scc1 .Lsf1
	s_cmp_lt_u32 s23, 3
	s_cbranch_scc1 .LBB0_414
	s_waitcnt vmcnt(6)
	ds_write_b128 v158, v[40:43]
	s_waitcnt vmcnt(5)
	ds_write_b128 v158, v[44:47] offset:10240
	s_waitcnt vmcnt(4)
	ds_write_b128 v159, v[56:59]

.LBB0_421:
	s_or_b64 exec, exec, s[18:19]
	v_add_u32_e32 v24, s22, v132
	v_add_u32_e32 v25, 0x1c0, v24
	v_cmp_gt_i32_e32 vcc, s21, v25
	v_add_u32_e32 v24, 0xc0, v24
	v_mov_b32_e32 v28, s3
	v_cndmask_b32_e32 v26, v117, v138, vcc
	v_add3_u32 v26, v156, v26, s20
	v_cndmask_b32_e32 v27, v24, v25, vcc
	v_mov_b32_e32 v24, s11
	v_add_u32_e32 v26, 0xfffff641, v26
	v_cndmask_b32_e64 v25, v24, 0, vcc
	v_mov_b32_e32 v24, s10
	v_cndmask_b32_e64 v26, v26, v27, s[6:7]
	v_cndmask_b32_e32 v24, v24, v28, vcc
	v_ashrrev_i32_e32 v27, 31, v26
	v_lshl_add_u64 v[24:25], v[24:25], 0, v[26:27]
	v_lshlrev_b64 v[24:25], 11, v[24:25]
	v_lshl_add_u64 v[24:25], s[8:9], 0, v[24:25]
	v_lshl_add_u64 v[28:29], v[24:25], 0, v[114:115]
	v_mov_b32_e32 v236, v28
	v_mov_b32_e32 v237, v29
	global_load_dwordx4 v[24:27], v[28:29], off offset:16
	s_nop 0
	global_load_dwordx4 v[28:31], v[28:29], off

; #define LAS __attribute__((address_space(3)))
; __device__ __forceinline__ void hgrn_scan(const Params& p, LAS unsigned char* lds, int chain) {
;     ...
; #pragma unroll
;         for (int blk = 0; blk < 8; ++blk) {
;             const f32x4 d4 = *(const LAS f32x4*)(bb + SB_D + (16 * blk + 4 * g) * 4);
;             f32x4 s = S[blk] * d4;
; #pragma unroll
;             for (int sp = 0; sp < 2; ++sp) {
;                 const LAS unsigned char* kp = bb + SB_KD + (16 * blk + li) * HPK + (32 * sp + 4 * g) * 2;
;                 s = __builtin_amdgcn_mfma_f32_16x16x32_bf16(cat8u(*(const LAS u32x2*)kp, *(const LAS u32x2*)(kp + 32)), vf[sp], s, 0, 0, 0);
;             }
;             S[blk] = s;
;         }
;         if (c + 1 < NCH) HS_STORE(c + 1, (uu + 1) & 1);
;         if (c + 3 < NCH) HS_LOAD(c + 3, (uu + 1) & 1);
.LBB0_426:
	v_add_u32_e32 v165, v153, v144
	v_add_u32_e32 v174, 0x1d200, v143
	ds_read_b128 v[180:183], v174 offset:0
	ds_read_b64 v[184:185], v165 offset:0
	ds_read_b64 v[186:187], v165 offset:32
	ds_read_b64 v[188:189], v165 offset:64
	ds_read_b64 v[190:191], v165 offset:96
	ds_read_b128 v[192:195], v174 offset:64
	ds_read_b64 v[196:197], v165 offset:2176
	ds_read_b64 v[198:199], v165 offset:2208
	ds_read_b64 v[200:201], v165 offset:2240
	ds_read_b64 v[202:203], v165 offset:2272
	s_waitcnt lgkmcnt(10)
	ds_read_b128 v[204:207], v174 offset:128
	ds_read_b64 v[208:209], v165 offset:4352
	ds_read_b64 v[210:211], v165 offset:4384
	ds_read_b64 v[212:213], v165 offset:4416
	ds_read_b64 v[214:215], v165 offset:4448
	s_waitcnt lgkmcnt(5)
	v_pk_mul_f32 v[76:77], v[76:77], v[180:181]
	v_pk_mul_f32 v[78:79], v[78:79], v[182:183]
	v_pk_mul_f32 v[92:93], v[92:93], v[192:193]
	v_pk_mul_f32 v[94:95], v[94:95], v[194:195]
	v_mfma_f32_16x16x32_bf16 v[76:79], v[184:187], v[100:103], v[76:79]
	s_nop 0
	v_mfma_f32_16x16x32_bf16 v[92:95], v[196:199], v[100:103], v[92:95]
	v_mfma_f32_16x16x32_bf16 v[76:79], v[188:191], v[96:99], v[76:79]
	v_mfma_f32_16x16x32_bf16 v[92:95], v[200:203], v[96:99], v[92:95]
	ds_read_b128 v[180:183], v174 offset:192
	ds_read_b64 v[184:185], v165 offset:6528
	ds_read_b64 v[186:187], v165 offset:6560
	ds_read_b64 v[188:189], v165 offset:6592
	ds_read_b64 v[190:191], v165 offset:6624
	ds_read_b128 v[192:195], v174 offset:256
	ds_read_b64 v[196:197], v165 offset:8704
	ds_read_b64 v[198:199], v165 offset:8736
	ds_read_b64 v[200:201], v165 offset:8768
	ds_read_b64 v[202:203], v165 offset:8800
	s_waitcnt lgkmcnt(5)
	v_pk_mul_f32 v[80:81], v[80:81], v[204:205]
	v_pk_mul_f32 v[82:83], v[82:83], v[206:207]
	v_pk_mul_f32 v[88:89], v[88:89], v[180:181]
	v_pk_mul_f32 v[90:91], v[90:91], v[182:183]
	v_mfma_f32_16x16x32_bf16 v[80:83], v[208:211], v[100:103], v[80:83]
	s_nop 0
	v_mfma_f32_16x16x32_bf16 v[88:91], v[184:187], v[100:103], v[88:91]
	v_mfma_f32_16x16x32_bf16 v[80:83], v[212:215], v[96:99], v[80:83]
	v_mfma_f32_16x16x32_bf16 v[88:91], v[188:191], v[96:99], v[88:91]
	ds_read_b128 v[204:207], v174 offset:320
	ds_read_b64 v[208:209], v165 offset:10880
	ds_read_b64 v[210:211], v165 offset:10912
	ds_read_b64 v[212:213], v165 offset:10944
	ds_read_b64 v[214:215], v165 offset:10976
	ds_read_b128 v[180:183], v174 offset:384
	ds_read_b64 v[184:185], v165 offset:13056
	ds_read_b64 v[186:187], v165 offset:13088
	ds_read_b64 v[188:189], v165 offset:13120
	ds_read_b64 v[190:191], v165 offset:13152
	s_waitcnt lgkmcnt(5)
	v_pk_mul_f32 v[72:73], v[72:73], v[192:193]
	v_pk_mul_f32 v[74:75], v[74:75], v[194:195]
	v_pk_mul_f32 v[84:85], v[84:85], v[204:205]
	v_pk_mul_f32 v[86:87], v[86:87], v[206:207]
	v_mfma_f32_16x16x32_bf16 v[72:75], v[196:199], v[100:103], v[72:75]
	s_nop 0
	v_mfma_f32_16x16x32_bf16 v[84:87], v[208:211], v[100:103], v[84:87]
	v_mfma_f32_16x16x32_bf16 v[72:75], v[200:203], v[96:99], v[72:75]
	v_mfma_f32_16x16x32_bf16 v[84:87], v[212:215], v[96:99], v[84:87]
	ds_read_b128 v[192:195], v174 offset:448
	ds_read_b64 v[196:197], v165 offset:15232
	ds_read_b64 v[198:199], v165 offset:15264
	ds_read_b64 v[200:201], v165 offset:15296
	ds_read_b64 v[202:203], v165 offset:15328
	s_waitcnt lgkmcnt(0)
	v_pk_mul_f32 v[64:65], v[64:65], v[180:181]
	v_pk_mul_f32 v[66:67], v[66:67], v[182:183]
	v_pk_mul_f32 v[68:69], v[68:69], v[192:193]
	v_pk_mul_f32 v[70:71], v[70:71], v[194:195]
	v_mfma_f32_16x16x32_bf16 v[64:67], v[184:187], v[100:103], v[64:67]
	s_nop 0
	v_mfma_f32_16x16x32_bf16 v[68:71], v[196:199], v[100:103], v[68:71]
	v_mfma_f32_16x16x32_bf16 v[64:67], v[188:191], v[96:99], v[64:67]
	v_mfma_f32_16x16x32_bf16 v[68:71], v[200:203], v[96:99], v[68:71]
	s_sub_u32 s97, s23, 6
	s_cmp_le_u32 s97, 24
	s_cbranch_scc1 .Lsf2
	s_add_i32 s12, s30, 3
	s_cmp_gt_u32 s12, 34
	s_cbranch_scc1 .LBB0_432
	s_cmp_eq_u32 s14, 0
	s_cbranch_scc1 .LBB0_429
	v_add_u32_e32 v96, v154, v113
	ds_write_b128 v96, v[48:51]
	ds_write_b128 v96, v[52:55] offset:10240
	ds_write_b128 v164, v[60:63] offset:40960

; __device__ __forceinline__ void hgrn_scan(const Params& p, LAS unsigned char* lds, int chain) {
;     ...
;         if (c + 1 < NCH) HS_STORE(c + 1, (uu + 1) & 1);
;         if (c + 3 < NCH) HS_LOAD(c + 3, (uu + 1) & 1);
.Lsf1:
	s_waitcnt vmcnt(15)
	ds_write_b128 v158, v[40:43]
	ds_write_b128 v158, v[44:47] offset:10240
	ds_write_b128 v159, v[56:59]
	v_add_u32_e32 v96, 0x2200, v160
	ds_write2_b64 v160, v[8:9], v[10:11] offset1:1
	ds_write2_b64 v96, v[12:13], v[14:15] offset1:1
	s_and_saveexec_b64 s[18:19], s[4:5]
	v_add_u32_e32 v96, 0x1d200, v134
	ds_write_b128 v96, v[4:7]
	s_or_b64 exec, exec, s[18:19]
	v_add_u32_e32 v96, v152, v112
	ds_write_b128 v96, v[28:31]
	v_add_u32_e32 v96, v152, v136
	ds_write_b128 v96, v[24:27]
	s_add_u32 s96, s34, s14
	s_addc_u32 s97, s35, s15
	s_add_u32 s98, s96, 0x14360000
	s_addc_u32 s99, s97, 0
	global_load_dwordx4 v[40:43], v240, s[98:99] offset:1536
	global_load_dwordx4 v[44:47], v241, s[98:99] offset:1536
	s_add_u32 s98, s96, 0x14368000
	s_addc_u32 s99, s97, 0
	s_and_saveexec_b64 s[18:19], s[100:101]
	global_load_dwordx4 v[56:59], v240, s[98:99] offset:1536
	s_mov_b64 exec, s[18:19]
	s_add_u32 s98, s96, 0x14364000
	s_addc_u32 s99, s97, 0
	global_load_dwordx4 v[8:11], v240, s[98:99] offset:1536
	global_load_dwordx4 v[12:15], v241, s[98:99] offset:1536
	s_and_saveexec_b64 s[18:19], s[4:5]
	s_cbranch_execz .Lsf1_d
	s_add_u32 s98, s96, 0x1436a000
	s_addc_u32 s99, s97, 0
	global_load_dwordx4 v[4:7], v240, s[98:99] offset:1536
.Lsf1_d:
	s_or_b64 exec, exec, s[18:19]
	v_lshl_add_u64 v[236:237], v[236:237], 0, s[36:37]
	global_load_dwordx4 v[24:27], v[236:237], off offset:16
	global_load_dwordx4 v[28:31], v[236:237], off
	s_branch .LBB0_422
.Lsf2:
	s_waitcnt vmcnt(15)
	v_add_u32_e32 v96, v154, v113
	ds_write_b128 v96, v[48:51]
	ds_write_b128 v96, v[52:55] offset:10240
	ds_write_b128 v164, v[60:63] offset:40960
	v_add_u32_e32 v96, 0x5000, v133
	ds_write2_b64 v96, v[16:17], v[18:19] offset1:1
	v_add_u32_e32 v96, 0x7200, v133
	ds_write2_b64 v96, v[20:21], v[22:23] offset1:1
	s_and_saveexec_b64 s[16:17], s[4:5]
	ds_write_b128 v134, v[0:3] offset:50176
	s_or_b64 exec, exec, s[16:17]
	ds_write_b128 v135, v[36:39] offset:50688
	ds_write_b128 v137, v[32:35] offset:50688
	s_add_u32 s96, s34, s14
	s_addc_u32 s97, s35, s15
	s_add_u32 s98, s96, 0x1436a000
	s_addc_u32 s99, s97, 0
	global_load_dwordx4 v[48:51], v240, s[98:99] offset:2048
	global_load_dwordx4 v[52:55], v241, s[98:99] offset:2048
	s_add_u32 s98, s96, 0x14372000
	s_addc_u32 s99, s97, 0
	s_and_saveexec_b64 s[16:17], s[100:101]
	global_load_dwordx4 v[60:63], v240, s[98:99] offset:2048
	s_mov_b64 exec, s[16:17]
	s_add_u32 s98, s96, 0x1436e000
	s_addc_u32 s99, s97, 0
	global_load_dwordx4 v[16:19], v240, s[98:99] offset:2048
	global_load_dwordx4 v[20:23], v241, s[98:99] offset:2048
	s_and_saveexec_b64 s[16:17], s[4:5]
	s_cbranch_execz .Lsf2_d
	s_add_u32 s98, s96, 0x14374000
	s_addc_u32 s99, s97, 0
	global_load_dwordx4 v[0:3], v240, s[98:99] offset:2048
.Lsf2_d:
	s_or_b64 exec, exec, s[16:17]
	v_lshl_add_u64 v[238:239], v[238:239], 0, s[36:37]
	global_load_dwordx4 v[32:35], v[238:239], off offset:16
	global_load_dwordx4 v[36:39], v[238:239], off
	s_branch .LBB0_407

; __device__ __forceinline__ int lane_id() { int l; asm volatile("v_mbcnt_lo_u32_b32 %0, -1, 0\n\tv_mbcnt_hi_u32_b32 %0, -1, %0" : "=v"(l)); return l; }
; #define LAS __attribute__((address_space(3)))
; __device__ __forceinline__ void phase_wconv_rest(const Params& p, LAS unsigned char* lds, int gw, int NGW) {
;     const int lane = lane_id(), wave = p.wave_id;
;     LAS float* scr = (LAS float*)(lds + 16384 + wave * 16384);
;     constexpr int I_A = (WA / 64) * (D_MODEL / 32), I_O = (D_MODEL / 64) * (D_MODEL / 32), I_1 = (D_MODEL / 64) * (FFN / 32), I_2 = (FFN / 64) * (D_MODEL / 32);
;     constexpr int NITEMS = 2 * I_A + I_O + 2 * I_1 + I_2;
;     unsigned char* ws = p.ws;
;     const float* sh2 = (const float*)(ws + WS_MOD) + 3 * D_MODEL; float* b2 = (float*)(ws + WS_BIAS2);
;     for (int it = gw; it < NITEMS; it += NGW) {
;         int r = it;
;         if (r < I_A) { transpose_item<false, false>(p.w_a, WA, D_MODEL, (bf16*)(ws + WS_WAT), 0, scr, r, lane); continue; } r -= I_A;
;         if (r < I_A) { transpose_item<false, false>(p.w_b, WA, D_MODEL, (bf16*)(ws + WS_WBT), 0, scr, r, lane); continue; } r -= I_A;
;         if (r < I_O) { transpose_item<false, false>(p.w_o, D_MODEL, D_MODEL, (bf16*)(ws + WS_WOT), 0, scr, r, lane); continue; } r -= I_O;
;         if (r < I_1) { transpose_item<false, true>(p.w1, D_MODEL, FFN, (bf16*)(ws + WS_W13T), 0, scr, r, lane, sh2, b2); continue; } r -= I_1;
;         if (r < I_1) { transpose_item<false, true>(p.w3, D_MODEL, FFN, (bf16*)(ws + WS_W13T), 128, scr, r, lane, sh2, b2); continue; } r -= I_1;
;         transpose_item<false, false>(p.w2, FFN, D_MODEL, (bf16*)(ws + WS_W2T), 0, scr, r, lane);
;     }
; __global__ void __launch_bounds__(NTHREADS, 2) mega_fwd(Params p_in) {
;     ...
;       const int nfree = nb - CTX_UNITS;
;       if (nfree >= 64) { if (bx >= CTX_UNITS) phase_wconv_rest(p, lds, (bx - CTX_UNITS) * 8 + wave_id, nfree * 8); }
;       else phase_wconv_rest(p, lds, bx * 8 + wave_id, nb * 8); }
.LBB0_505:
	s_branch .Lw2_skip
.Lw2_first:
	s_cmpk_lg_i32 s33, 0x100
	s_cbranch_scc1 .LBB0_436
	s_waitcnt lgkmcnt(0)
	v_writelane_b32 v250, s3, 40
	v_writelane_b32 v250, s12, 41
	v_writelane_b32 v250, s18, 42
	v_writelane_b32 v250, s19, 43
	v_writelane_b32 v250, s20, 44
	v_writelane_b32 v250, s21, 45
	v_writelane_b32 v250, s22, 46
	v_writelane_b32 v250, s23, 47
	v_writelane_b32 v250, s24, 48
	v_writelane_b32 v250, s25, 49
	v_writelane_b32 v250, s26, 50
	v_writelane_b32 v250, s27, 51
	s_lshr_b32 s3, s76, 6
	s_load_dwordx8 s[8:15], s[0:1], 0x70
	s_load_dwordx2 s[40:41], s[0:1], 0x90
	s_load_dwordx2 s[42:43], s[0:1], 0xa8
	s_load_dwordx2 s[22:23], s[0:1], 0xb8
	s_waitcnt vmcnt(0) lgkmcnt(0)
	s_barrier
	s_sub_i32 s4, s2, 64
	s_mul_hi_u32 s96, s4, 0x55555556
	s_mul_i32 s97, s96, 3
	s_sub_i32 s97, s4, s97
	s_cmp_eq_u32 s97, 2
	s_cbranch_scc1 .Lw2_classb
	s_lshl_b32 s4, s96, 1
	s_add_i32 s4, s4, s97
	s_lshl_b32 s4, s4, 3
	s_add_i32 s4, s4, s3
	s_add_i32 s20, s4, 0x3c80
	s_movk_i32 s21, 0x400
	s_movk_i32 s97, 0x467f
	s_branch .Lw2_classdone
.Lw2_classb:
	s_lshl_b32 s4, s96, 3
	s_add_i32 s4, s4, s3
	s_add_i32 s20, s4, 0x4680
	s_movk_i32 s21, 0x200
	s_movk_i32 s97, 0x51ff
.Lw2_classdone:
	s_cmp_gt_i32 s20, s97
	v_mbcnt_lo_u32_b32 v0, -1, 0
	v_mbcnt_hi_u32_b32 v0, -1, v0
	s_cbranch_scc1 .Lw2_done
	s_waitcnt lgkmcnt(0)
	s_add_u32 s6, s22, 0x106000
	s_addc_u32 s7, s23, 0
	s_add_u32 s16, s22, 0x18000
	s_addc_u32 s17, s23, 0
	s_lshl_b32 s3, s3, 14
	v_ashrrev_i32_e32 v34, 5, v0
	v_lshlrev_b32_e32 v1, 2, v0
	s_movk_i32 s4, 0x84
	s_add_i32 s3, s3, 0
	v_and_b32_e32 v22, 0x7c, v1
	v_mul_lo_u32 v1, v34, s4
	v_add3_u32 v26, s3, v22, v1
	v_lshlrev_b32_e32 v1, 3, v0
	v_and_b32_e32 v1, 56, v1
	v_ashrrev_i32_e32 v35, 3, v0
	v_lshlrev_b32_e32 v12, 1, v1
	v_mov_b32_e32 v13, 0
	v_mul_u32_u24_e32 v4, 0x84, v1
	v_lshl_add_u64 v[10:11], s[22:23], 0, v[12:13]
	v_lshlrev_b32_e32 v1, 2, v35
	s_mov_b64 s[22:23], 0x142000
	v_add3_u32 v27, s3, v4, v1
	v_lshl_add_u64 v[4:5], v[10:11], 0, s[22:23]
	s_mov_b64 s[22:23], 0x4b42000
	v_lshl_add_u64 v[6:7], v[10:11], 0, s[22:23]
	s_mov_b64 s[22:23], 0x4742000
	s_mov_b64 s[4:5], 0x2d42000
	v_ashrrev_i32_e32 v1, 31, v0
	v_lshl_add_u64 v[8:9], v[10:11], 0, s[22:23]
	s_mov_b64 s[22:23], 0x4342000
	v_mov_b32_e32 v23, v13
	s_mov_b32 s19, 0
	v_lshl_add_u64 v[2:3], v[10:11], 0, s[4:5]
	v_add_u32_e32 v36, 8, v35
	v_add_u32_e32 v37, 16, v35
	v_add_u32_e32 v38, 24, v35
	v_cmp_gt_i32_e64 s[4:5], 32, v0
	v_lshl_add_u64 v[10:11], v[10:11], 0, s[22:23]
	v_lshl_add_u64 v[12:13], s[42:43], 0, v[22:23]
	v_lshl_add_u64 v[14:15], s[40:41], 0, v[22:23]
	v_lshl_add_u64 v[16:17], s[14:15], 0, v[22:23]
	v_lshl_add_u64 v[18:19], s[12:13], 0, v[22:23]
	v_lshl_add_u64 v[20:21], s[10:11], 0, v[22:23]
	v_lshl_add_u64 v[22:23], s[8:9], 0, v[22:23]
	v_lshl_add_u64 v[24:25], v[0:1], 2, s[16:17]
	s_lshl_b32 s3, s20, 5
	s_lshl_b32 s12, s21, 5
	s_mov_b32 s13, 0xc000
	s_mov_b32 s14, 0x18000
	s_mov_b32 s15, 0x24000
	s_movk_i32 s22, 0x2c00
	s_movk_i32 s23, 0x5800
	v_add_u32_e32 v39, 0x4000, v26
	v_add_u32_e32 v40, 0x4400, v26
	v_add_u32_e32 v41, 0x4800, v26
	v_add_u32_e32 v42, 0x4c00, v26
	v_add_u32_e32 v43, 0x5000, v26
	v_add_u32_e32 v44, 0x5400, v26
	v_add_u32_e32 v45, 0x5800, v26
	v_add_u32_e32 v46, 0x5c00, v26
	v_add_u32_e32 v47, 0x4000, v27
	s_branch .Lw2c_244
.Lw2c_243:
	s_add_i32 s20, s20, s21
	s_add_i32 s3, s3, s12
	s_cmp_gt_i32 s20, s97
	s_cbranch_scc1 .Lw2_done

; __global__ void __launch_bounds__(NTHREADS, 2) mega_fwd(Params p_in) {
;     ...
;       const int nfree = nb - CTX_UNITS;
;       if (nfree >= 64) { if (bx >= CTX_UNITS) phase_wconv_rest(p, lds, (bx - CTX_UNITS) * 8 + wave_id, nfree * 8); }
;       else phase_wconv_rest(p, lds, bx * 8 + wave_id, nb * 8); }
.Lw2_done:
	v_readlane_b32 s3, v250, 40
	v_readlane_b32 s12, v250, 41
	v_readlane_b32 s18, v250, 42
	v_readlane_b32 s19, v250, 43
	v_readlane_b32 s20, v250, 44
	v_readlane_b32 s21, v250, 45
	v_readlane_b32 s22, v250, 46
	v_readlane_b32 s23, v250, 47
	v_readlane_b32 s24, v250, 48
	v_readlane_b32 s25, v250, 49
	v_readlane_b32 s26, v250, 50
	v_readlane_b32 s27, v250, 51
	s_nop 4
	s_branch .LBB0_436
